# attention epilogue split across both wave halves: halves swap 32 partials each via LDS, all 8 waves merge+gate+store 32 outputs per lane (was: waves 0-3 do all 64, waves 4-7 idle)
# baseline (speedup 1.0000x reference)
; #define LAS __attribute__((address_space(3)))
; DI void attn_unit(const Params& p, int b, int h, int qb, LAS unsigned char* lds, int tid, int lane, int wave) {
;     ...
;     { const u32x2 sw_ = __builtin_amdgcn_permlane32_swap(__float_as_uint(lrow), __float_as_uint(lrow), false, false); lrow = __uint_as_float(sw_.x) + __uint_as_float(sw_.y); }
;     LAS float* MB = (LAS float*)(lds + AT_MB) + w4 * 66 * 64 + lane;
;     if (g == 1) {
; #pragma unroll
;         for (int i = 0; i < 4; ++i)
; #pragma unroll
;             for (int j = 0; j < 16; ++j) MB[(i * 16 + j) * 64] = o[i][j];
;         MB[64 * 64] = mrow; MB[65 * 64] = lrow;
;     }
;     __syncthreads();
;     if (g == 0) {
;         const float m1 = MB[64 * 64], l1 = MB[65 * 64];
;         const float m = fmaxf(mrow, m1);
;         const float a0 = __builtin_amdgcn_exp2f(mrow - m), a1 = __builtin_amdgcn_exp2f(m1 - m);
;         const float inv = 1.0f / (lrow * a0 + l1 * a1);
;         const size_t tok = tokb + qr0 + r;
;         const bf16_t* gp = Z + tok * ZLD + Z_MG + h * 128 + 4 * hh;
;         bf16_t* op = OB + tok * DM + 512 + h * 128 + 4 * hh;
;         u32x2 gw[4][4];
; #pragma unroll
;         for (int i = 0; i < 4; ++i)
; #pragma unroll
;             for (int q = 0; q < 4; ++q) gw[i][q] = *(const u32x2*)(gp + i * 32 + q * 8);
.LBB0_440:
	v_mov_b32_e32 v0, v203
	s_mulk_i32 s20, 0x4400
	s_nop 0
	v_permlane32_swap_b32_e32 v203, v0
	s_add_i32 s0, s20, 0
	v_add_f32_e32 v68, v203, v0
	s_cmp_lg_u32 s21, 1
	v_lshl_add_u32 v104, v183, 2, s0
	s_barrier
	s_cmp_lg_u32 s21, 0
	s_cbranch_scc1 .Le1_wb
	ds_write2st64_b32 v104, v18, v19 offset0:0 offset1:1
	ds_write2st64_b32 v104, v20, v21 offset0:2 offset1:3
	ds_write2st64_b32 v104, v22, v23 offset0:4 offset1:5
	ds_write2st64_b32 v104, v24, v25 offset0:6 offset1:7
	ds_write2st64_b32 v104, v26, v27 offset0:8 offset1:9
	ds_write2st64_b32 v104, v28, v29 offset0:10 offset1:11
	ds_write2st64_b32 v104, v30, v31 offset0:12 offset1:13
	ds_write2st64_b32 v104, v32, v33 offset0:14 offset1:15
	ds_write2st64_b32 v104, v2, v3 offset0:16 offset1:17
	ds_write2st64_b32 v104, v4, v5 offset0:18 offset1:19
	ds_write2st64_b32 v104, v6, v7 offset0:20 offset1:21
	ds_write2st64_b32 v104, v8, v9 offset0:22 offset1:23
	ds_write2st64_b32 v104, v10, v11 offset0:24 offset1:25
	ds_write2st64_b32 v104, v12, v13 offset0:26 offset1:27
	ds_write2st64_b32 v104, v14, v15 offset0:28 offset1:29
	ds_write2st64_b32 v104, v16, v17 offset0:30 offset1:31
	ds_write2st64_b32 v104, v204, v68 offset0:32 offset1:33
	s_branch .Le1_wd
.Le1_wb:
	ds_write2st64_b32 v104, v50, v51 offset0:34 offset1:35
	ds_write2st64_b32 v104, v52, v53 offset0:36 offset1:37
	ds_write2st64_b32 v104, v54, v55 offset0:38 offset1:39
	ds_write2st64_b32 v104, v56, v57 offset0:40 offset1:41
	ds_write2st64_b32 v104, v58, v59 offset0:42 offset1:43
	ds_write2st64_b32 v104, v60, v61 offset0:44 offset1:45
	ds_write2st64_b32 v104, v62, v63 offset0:46 offset1:47
	ds_write2st64_b32 v104, v64, v65 offset0:48 offset1:49
	ds_write2st64_b32 v104, v34, v35 offset0:50 offset1:51
	ds_write2st64_b32 v104, v36, v37 offset0:52 offset1:53
	ds_write2st64_b32 v104, v38, v39 offset0:54 offset1:55
	ds_write2st64_b32 v104, v40, v41 offset0:56 offset1:57
	ds_write2st64_b32 v104, v42, v43 offset0:58 offset1:59
	ds_write2st64_b32 v104, v44, v45 offset0:60 offset1:61
	ds_write2st64_b32 v104, v46, v47 offset0:62 offset1:63
	ds_write2st64_b32 v104, v48, v49 offset0:64 offset1:65
	ds_write2st64_b32 v104, v204, v68 offset0:66 offset1:67
	s_waitcnt lgkmcnt(0)
	v_mov_b64_e32 v[50:51], v[18:19]
	v_mov_b64_e32 v[52:53], v[20:21]
	v_mov_b64_e32 v[54:55], v[22:23]
	v_mov_b64_e32 v[56:57], v[24:25]
	v_mov_b64_e32 v[58:59], v[26:27]
	v_mov_b64_e32 v[60:61], v[28:29]
	v_mov_b64_e32 v[62:63], v[30:31]
	v_mov_b64_e32 v[64:65], v[32:33]
	v_mov_b64_e32 v[34:35], v[2:3]
	v_mov_b64_e32 v[36:37], v[4:5]
	v_mov_b64_e32 v[38:39], v[6:7]
	v_mov_b64_e32 v[40:41], v[8:9]
	v_mov_b64_e32 v[42:43], v[10:11]
	v_mov_b64_e32 v[44:45], v[12:13]
	v_mov_b64_e32 v[46:47], v[14:15]
	v_mov_b64_e32 v[48:49], v[16:17]
.Le1_wd:
	s_xor_b32 s0, s21, 1
	s_mulk_i32 s0, 0x2200
	v_add_u32_e32 v150, s0, v104
	s_waitcnt lgkmcnt(0)
	s_barrier
	ds_read2st64_b32 v[70:71], v150 offset0:32 offset1:33
	ds_read2st64_b32 v[110:111], v150 offset0:0 offset1:1
	ds_read2st64_b32 v[112:113], v150 offset0:2 offset1:3
	ds_read2st64_b32 v[114:115], v150 offset0:4 offset1:5
	ds_read2st64_b32 v[116:117], v150 offset0:6 offset1:7
	ds_read2st64_b32 v[118:119], v150 offset0:8 offset1:9
	ds_read2st64_b32 v[120:121], v150 offset0:10 offset1:11
	ds_read2st64_b32 v[122:123], v150 offset0:12 offset1:13
	ds_read2st64_b32 v[124:125], v150 offset0:14 offset1:15
	ds_read2st64_b32 v[126:127], v150 offset0:16 offset1:17
	ds_read2st64_b32 v[128:129], v150 offset0:18 offset1:19
	ds_read2st64_b32 v[130:131], v150 offset0:20 offset1:21
	ds_read2st64_b32 v[132:133], v150 offset0:22 offset1:23
	ds_read2st64_b32 v[134:135], v150 offset0:24 offset1:25
	ds_read2st64_b32 v[136:137], v150 offset0:26 offset1:27
	ds_read2st64_b32 v[138:139], v150 offset0:28 offset1:29
	ds_read2st64_b32 v[140:141], v150 offset0:30 offset1:31
	v_max_f32_e32 v0, v204, v204
	s_lshl_b32 s0, s2, 8
	s_mov_b32 s1, s93
	v_ashrrev_i32_e32 v183, 31, v182
	s_waitcnt lgkmcnt(0)
	v_max_f32_e32 v66, v70, v70
	v_max_f32_e32 v0, v0, v66
	v_sub_f32_e32 v66, v204, v0
	v_sub_f32_e32 v0, v70, v0
	v_exp_f32_e32 v66, v66
	v_exp_f32_e32 v67, v0
	v_mov_b32_e32 v69, v71
	v_lshlrev_b32_e32 v0, 12, v202
	v_lshlrev_b64 v[102:103], 1, v[182:183]
	v_pk_mul_f32 v[68:69], v[68:69], v[66:67]
	s_mov_b64 s[4:5], 0x4600c00
	v_add_f32_e32 v105, v68, v69
	v_lshl_add_u64 v[68:69], s[50:51], 0, v[0:1]
	v_lshl_add_u64 v[70:71], v[68:69], 0, s[0:1]
	v_lshlrev_b32_e32 v0, 11, v202
	v_lshl_add_u64 v[70:71], v[70:71], 0, v[102:103]
	v_sub_co_u32_e32 v72, vcc, 0, v0
	v_lshl_add_u64 v[106:107], v[70:71], 0, s[4:5]
	s_nop 0
	v_subb_co_u32_e64 v73, s[4:5], 0, 0, vcc
	v_lshl_add_u64 v[68:69], v[68:69], 0, v[72:73]
	v_lshl_add_u64 v[68:69], v[68:69], 0, s[0:1]
	s_mov_b32 s0, 0x4600000
	v_add_co_u32_e32 v70, vcc, s0, v70
	v_div_scale_f32 v0, s[0:1], v105, v105, 1.0
	s_nop 0
	v_addc_co_u32_e32 v71, vcc, 0, v71, vcc
	s_lshl_b32 vcc_lo, s21, 7
	s_mov_b32 vcc_hi, 0
	v_lshl_add_u64 v[142:143], v[106:107], 0, vcc
	v_lshl_add_u32 v152, v182, 1, vcc_lo
	global_load_dwordx2 v[74:75], v[142:143], off
	global_load_dwordx2 v[76:77], v[142:143], off offset:16
	global_load_dwordx2 v[78:79], v[142:143], off offset:32
	global_load_dwordx2 v[80:81], v[142:143], off offset:48
	global_load_dwordx2 v[82:83], v[142:143], off offset:64
	global_load_dwordx2 v[84:85], v[142:143], off offset:80
	global_load_dwordx2 v[86:87], v[142:143], off offset:96
	global_load_dwordx2 v[88:89], v[142:143], off offset:112
	v_rcp_f32_e32 v106, v0
	v_lshl_add_u64 v[102:103], v[68:69], 0, v[102:103]
	s_mov_b64 s[0:1], 0xae00400
	v_lshl_add_u64 v[68:69], v[102:103], 0, s[0:1]
	v_fma_f32 v107, -v0, v106, 1.0
	v_fmac_f32_e32 v106, v107, v106
	v_div_scale_f32 v107, vcc, 1.0, v105, 1.0
	v_mul_f32_e32 v108, v107, v106
	v_fma_f32 v109, -v0, v108, v107
	v_fmac_f32_e32 v108, v109, v106
	v_fma_f32 v0, -v0, v108, v107
	v_div_fmas_f32 v0, v0, v106, v108
	v_div_fixup_f32 v0, v0, v105, 1.0
	v_mov_b32_e32 v72, v67
	v_mov_b32_e32 v153, 0
	v_lshl_add_u64 v[148:149], v[152:153], 0, v[68:69]
	s_waitcnt vmcnt(6)
; DI unsigned pk2(float lo, float hi) { f32x2 v = {lo, hi}; return __builtin_bit_cast(unsigned, __builtin_convertvector(v, bf2_t)); }
; DI float bflo(unsigned w) { return __uint_as_float(w << 16); }
; DI float bfhi(unsigned w) { return __uint_as_float(w & 0xffff0000u); }
; DI void attn_unit(const Params& p, int b, int h, int qb, LAS unsigned char* lds, int tid, int lane, int wave) {
;     ...
; #pragma unroll
;         for (int i = 0; i < 4; ++i)
; #pragma unroll
;             for (int q = 0; q < 4; ++q) {
;                 float gv[4] = {bflo(gw[i][q].x), bfhi(gw[i][q].x), bflo(gw[i][q].y), bfhi(gw[i][q].y)}; float ov[4];
; #pragma unroll
;                 for (int e = 0; e < 4; ++e) { const float val = (o[i][q * 4 + e] * a0 + MB[(i * 16 + q * 4 + e) * 64] * a1) * inv; ov[e] = val * (gv[e] / (1.f + __expf(-gv[e]))); }
;                 *(u32x2*)(op + i * 32 + q * 8) = (u32x2){pk2(ov[0], ov[1]), pk2(ov[2], ov[3])};
;             }
	v_pk_mul_f32 v[154:155], v[72:73], v[110:111] op_sel_hi:[0,1]
	v_pk_mul_f32 v[156:157], v[72:73], v[112:113] op_sel_hi:[0,1]
	v_pk_mul_f32 v[158:159], v[72:73], v[114:115] op_sel_hi:[0,1]
	v_pk_mul_f32 v[160:161], v[72:73], v[116:117] op_sel_hi:[0,1]
	v_lshlrev_b32_e32 v162, 16, v74
	v_and_b32_e32 v163, 0xffff0000, v74
	v_lshlrev_b32_e32 v164, 16, v75
	v_and_b32_e32 v165, 0xffff0000, v75
	v_lshlrev_b32_e32 v166, 16, v76
	v_and_b32_e32 v167, 0xffff0000, v76
	v_lshlrev_b32_e32 v168, 16, v77
	v_and_b32_e32 v169, 0xffff0000, v77
	v_pk_fma_f32 v[154:155], v[50:51], v[66:67], v[154:155] op_sel_hi:[1,0,1]
	v_pk_fma_f32 v[156:157], v[52:53], v[66:67], v[156:157] op_sel_hi:[1,0,1]
	v_pk_fma_f32 v[158:159], v[54:55], v[66:67], v[158:159] op_sel_hi:[1,0,1]
	v_pk_fma_f32 v[160:161], v[56:57], v[66:67], v[160:161] op_sel_hi:[1,0,1]
	v_mul_f32_e32 v170, 0xbfb8aa3b, v162
	v_mul_f32_e32 v171, 0xbfb8aa3b, v163
	v_mul_f32_e32 v172, 0xbfb8aa3b, v164
	v_mul_f32_e32 v173, 0xbfb8aa3b, v165
	v_mul_f32_e32 v174, 0xbfb8aa3b, v166
	v_mul_f32_e32 v175, 0xbfb8aa3b, v167
	v_mul_f32_e32 v176, 0xbfb8aa3b, v168
	v_mul_f32_e32 v177, 0xbfb8aa3b, v169
	v_pk_mul_f32 v[154:155], v[0:1], v[154:155] op_sel_hi:[0,1]
	v_pk_mul_f32 v[156:157], v[0:1], v[156:157] op_sel_hi:[0,1]
	v_pk_mul_f32 v[158:159], v[0:1], v[158:159] op_sel_hi:[0,1]
	v_pk_mul_f32 v[160:161], v[0:1], v[160:161] op_sel_hi:[0,1]
	v_exp_f32_e32 v170, v170
	v_exp_f32_e32 v171, v171
	v_exp_f32_e32 v172, v172
	v_exp_f32_e32 v173, v173
	v_exp_f32_e32 v174, v174
	v_exp_f32_e32 v175, v175
	v_exp_f32_e32 v176, v176
	v_exp_f32_e32 v177, v177
	v_pk_add_f32 v[170:171], v[170:171], 1.0 op_sel_hi:[1,0]
	v_pk_add_f32 v[172:173], v[172:173], 1.0 op_sel_hi:[1,0]
	v_pk_add_f32 v[174:175], v[174:175], 1.0 op_sel_hi:[1,0]
	v_pk_add_f32 v[176:177], v[176:177], 1.0 op_sel_hi:[1,0]
	v_rcp_f32_e32 v170, v170
	v_rcp_f32_e32 v171, v171
	v_rcp_f32_e32 v172, v172
	v_rcp_f32_e32 v173, v173
	v_rcp_f32_e32 v174, v174
	v_rcp_f32_e32 v175, v175
	v_rcp_f32_e32 v176, v176
	v_rcp_f32_e32 v177, v177
	v_pk_mul_f32 v[162:163], v[162:163], v[170:171]
	v_pk_mul_f32 v[164:165], v[164:165], v[172:173]
	v_pk_mul_f32 v[166:167], v[166:167], v[174:175]
	v_pk_mul_f32 v[168:169], v[168:169], v[176:177]
	v_pk_mul_f32 v[154:155], v[162:163], v[154:155]
	v_pk_mul_f32 v[156:157], v[164:165], v[156:157]
	v_pk_mul_f32 v[158:159], v[166:167], v[158:159]
	v_pk_mul_f32 v[160:161], v[168:169], v[160:161]
	v_cvt_pk_bf16_f32 v90, v154, v155
	v_cvt_pk_bf16_f32 v91, v156, v157
	v_cvt_pk_bf16_f32 v92, v158, v159
	v_cvt_pk_bf16_f32 v93, v160, v161
	s_nop 1
	v_permlane32_swap_b32_e32 v90, v92
	v_permlane32_swap_b32_e32 v91, v93
	global_store_dwordx4 v[148:149], v[90:93], off
	s_waitcnt vmcnt(5)
	v_pk_mul_f32 v[154:155], v[72:73], v[118:119] op_sel_hi:[0,1]
	v_pk_mul_f32 v[156:157], v[72:73], v[120:121] op_sel_hi:[0,1]
	v_pk_mul_f32 v[158:159], v[72:73], v[122:123] op_sel_hi:[0,1]
	v_pk_mul_f32 v[160:161], v[72:73], v[124:125] op_sel_hi:[0,1]
	v_lshlrev_b32_e32 v162, 16, v78
	v_and_b32_e32 v163, 0xffff0000, v78
	v_lshlrev_b32_e32 v164, 16, v79
	v_and_b32_e32 v165, 0xffff0000, v79
	v_lshlrev_b32_e32 v166, 16, v80
	v_and_b32_e32 v167, 0xffff0000, v80
	v_lshlrev_b32_e32 v168, 16, v81
	v_and_b32_e32 v169, 0xffff0000, v81
	v_pk_fma_f32 v[154:155], v[58:59], v[66:67], v[154:155] op_sel_hi:[1,0,1]
	v_pk_fma_f32 v[156:157], v[60:61], v[66:67], v[156:157] op_sel_hi:[1,0,1]
	v_pk_fma_f32 v[158:159], v[62:63], v[66:67], v[158:159] op_sel_hi:[1,0,1]
	v_pk_fma_f32 v[160:161], v[64:65], v[66:67], v[160:161] op_sel_hi:[1,0,1]
	v_mul_f32_e32 v170, 0xbfb8aa3b, v162
	v_mul_f32_e32 v171, 0xbfb8aa3b, v163
	v_mul_f32_e32 v172, 0xbfb8aa3b, v164
	v_mul_f32_e32 v173, 0xbfb8aa3b, v165
	v_mul_f32_e32 v174, 0xbfb8aa3b, v166
	v_mul_f32_e32 v175, 0xbfb8aa3b, v167
	v_mul_f32_e32 v176, 0xbfb8aa3b, v168
	v_mul_f32_e32 v177, 0xbfb8aa3b, v169
	v_pk_mul_f32 v[154:155], v[0:1], v[154:155] op_sel_hi:[0,1]
	v_pk_mul_f32 v[156:157], v[0:1], v[156:157] op_sel_hi:[0,1]
	v_pk_mul_f32 v[158:159], v[0:1], v[158:159] op_sel_hi:[0,1]
	v_pk_mul_f32 v[160:161], v[0:1], v[160:161] op_sel_hi:[0,1]
	v_exp_f32_e32 v170, v170
	v_exp_f32_e32 v171, v171
	v_exp_f32_e32 v172, v172
	v_exp_f32_e32 v173, v173
	v_exp_f32_e32 v174, v174
	v_exp_f32_e32 v175, v175
	v_exp_f32_e32 v176, v176
	v_exp_f32_e32 v177, v177
	v_pk_add_f32 v[170:171], v[170:171], 1.0 op_sel_hi:[1,0]
	v_pk_add_f32 v[172:173], v[172:173], 1.0 op_sel_hi:[1,0]
	v_pk_add_f32 v[174:175], v[174:175], 1.0 op_sel_hi:[1,0]
	v_pk_add_f32 v[176:177], v[176:177], 1.0 op_sel_hi:[1,0]
	v_rcp_f32_e32 v170, v170
	v_rcp_f32_e32 v171, v171
	v_rcp_f32_e32 v172, v172
	v_rcp_f32_e32 v173, v173
	v_rcp_f32_e32 v174, v174
	v_rcp_f32_e32 v175, v175
	v_rcp_f32_e32 v176, v176
	v_rcp_f32_e32 v177, v177
	v_pk_mul_f32 v[162:163], v[162:163], v[170:171]
	v_pk_mul_f32 v[164:165], v[164:165], v[172:173]
	v_pk_mul_f32 v[166:167], v[166:167], v[174:175]
	v_pk_mul_f32 v[168:169], v[168:169], v[176:177]
	v_pk_mul_f32 v[154:155], v[162:163], v[154:155]
	v_pk_mul_f32 v[156:157], v[164:165], v[156:157]
	v_pk_mul_f32 v[158:159], v[166:167], v[158:159]
	v_pk_mul_f32 v[160:161], v[168:169], v[160:161]
	v_cvt_pk_bf16_f32 v94, v154, v155
	v_cvt_pk_bf16_f32 v95, v156, v157
	v_cvt_pk_bf16_f32 v96, v158, v159
	v_cvt_pk_bf16_f32 v97, v160, v161
	s_nop 1
	v_permlane32_swap_b32_e32 v94, v96
	v_permlane32_swap_b32_e32 v95, v97
	global_store_dwordx4 v[148:149], v[94:97], off offset:32
	s_waitcnt vmcnt(4)
; DI unsigned pk2(float lo, float hi) { f32x2 v = {lo, hi}; return __builtin_bit_cast(unsigned, __builtin_convertvector(v, bf2_t)); }
; DI float bflo(unsigned w) { return __uint_as_float(w << 16); }
; DI float bfhi(unsigned w) { return __uint_as_float(w & 0xffff0000u); }
; DI void attn_unit(const Params& p, int b, int h, int qb, LAS unsigned char* lds, int tid, int lane, int wave) {
;     ...
; #pragma unroll
;         for (int i = 0; i < 4; ++i)
; #pragma unroll
;             for (int q = 0; q < 4; ++q) {
;                 float gv[4] = {bflo(gw[i][q].x), bfhi(gw[i][q].x), bflo(gw[i][q].y), bfhi(gw[i][q].y)}; float ov[4];
; #pragma unroll
;                 for (int e = 0; e < 4; ++e) { const float val = (o[i][q * 4 + e] * a0 + MB[(i * 16 + q * 4 + e) * 64] * a1) * inv; ov[e] = val * (gv[e] / (1.f + __expf(-gv[e]))); }
;                 *(u32x2*)(op + i * 32 + q * 8) = (u32x2){pk2(ov[0], ov[1]), pk2(ov[2], ov[3])};
;             }
	v_pk_mul_f32 v[154:155], v[72:73], v[126:127] op_sel_hi:[0,1]
	v_pk_mul_f32 v[156:157], v[72:73], v[128:129] op_sel_hi:[0,1]
	v_pk_mul_f32 v[158:159], v[72:73], v[130:131] op_sel_hi:[0,1]
	v_pk_mul_f32 v[160:161], v[72:73], v[132:133] op_sel_hi:[0,1]
	v_lshlrev_b32_e32 v162, 16, v82
	v_and_b32_e32 v163, 0xffff0000, v82
	v_lshlrev_b32_e32 v164, 16, v83
	v_and_b32_e32 v165, 0xffff0000, v83
	v_lshlrev_b32_e32 v166, 16, v84
	v_and_b32_e32 v167, 0xffff0000, v84
	v_lshlrev_b32_e32 v168, 16, v85
	v_and_b32_e32 v169, 0xffff0000, v85
	v_pk_fma_f32 v[154:155], v[34:35], v[66:67], v[154:155] op_sel_hi:[1,0,1]
	v_pk_fma_f32 v[156:157], v[36:37], v[66:67], v[156:157] op_sel_hi:[1,0,1]
	v_pk_fma_f32 v[158:159], v[38:39], v[66:67], v[158:159] op_sel_hi:[1,0,1]
	v_pk_fma_f32 v[160:161], v[40:41], v[66:67], v[160:161] op_sel_hi:[1,0,1]
	v_mul_f32_e32 v170, 0xbfb8aa3b, v162
	v_mul_f32_e32 v171, 0xbfb8aa3b, v163
	v_mul_f32_e32 v172, 0xbfb8aa3b, v164
	v_mul_f32_e32 v173, 0xbfb8aa3b, v165
	v_mul_f32_e32 v174, 0xbfb8aa3b, v166
	v_mul_f32_e32 v175, 0xbfb8aa3b, v167
	v_mul_f32_e32 v176, 0xbfb8aa3b, v168
	v_mul_f32_e32 v177, 0xbfb8aa3b, v169
	v_pk_mul_f32 v[154:155], v[0:1], v[154:155] op_sel_hi:[0,1]
	v_pk_mul_f32 v[156:157], v[0:1], v[156:157] op_sel_hi:[0,1]
	v_pk_mul_f32 v[158:159], v[0:1], v[158:159] op_sel_hi:[0,1]
	v_pk_mul_f32 v[160:161], v[0:1], v[160:161] op_sel_hi:[0,1]
	v_exp_f32_e32 v170, v170
	v_exp_f32_e32 v171, v171
	v_exp_f32_e32 v172, v172
	v_exp_f32_e32 v173, v173
	v_exp_f32_e32 v174, v174
	v_exp_f32_e32 v175, v175
	v_exp_f32_e32 v176, v176
	v_exp_f32_e32 v177, v177
	v_pk_add_f32 v[170:171], v[170:171], 1.0 op_sel_hi:[1,0]
	v_pk_add_f32 v[172:173], v[172:173], 1.0 op_sel_hi:[1,0]
	v_pk_add_f32 v[174:175], v[174:175], 1.0 op_sel_hi:[1,0]
	v_pk_add_f32 v[176:177], v[176:177], 1.0 op_sel_hi:[1,0]
	v_rcp_f32_e32 v170, v170
	v_rcp_f32_e32 v171, v171
	v_rcp_f32_e32 v172, v172
	v_rcp_f32_e32 v173, v173
	v_rcp_f32_e32 v174, v174
	v_rcp_f32_e32 v175, v175
	v_rcp_f32_e32 v176, v176
	v_rcp_f32_e32 v177, v177
	v_pk_mul_f32 v[162:163], v[162:163], v[170:171]
	v_pk_mul_f32 v[164:165], v[164:165], v[172:173]
	v_pk_mul_f32 v[166:167], v[166:167], v[174:175]
	v_pk_mul_f32 v[168:169], v[168:169], v[176:177]
	v_pk_mul_f32 v[154:155], v[162:163], v[154:155]
	v_pk_mul_f32 v[156:157], v[164:165], v[156:157]
	v_pk_mul_f32 v[158:159], v[166:167], v[158:159]
	v_pk_mul_f32 v[160:161], v[168:169], v[160:161]
	v_cvt_pk_bf16_f32 v98, v154, v155
	v_cvt_pk_bf16_f32 v99, v156, v157
	v_cvt_pk_bf16_f32 v100, v158, v159
	v_cvt_pk_bf16_f32 v101, v160, v161
	s_nop 1
	v_permlane32_swap_b32_e32 v98, v100
	v_permlane32_swap_b32_e32 v99, v101
	global_store_dwordx4 v[148:149], v[98:101], off offset:64
	s_waitcnt vmcnt(3)
	v_pk_mul_f32 v[154:155], v[72:73], v[134:135] op_sel_hi:[0,1]
	v_pk_mul_f32 v[156:157], v[72:73], v[136:137] op_sel_hi:[0,1]
	v_pk_mul_f32 v[158:159], v[72:73], v[138:139] op_sel_hi:[0,1]
	v_pk_mul_f32 v[160:161], v[72:73], v[140:141] op_sel_hi:[0,1]
	v_lshlrev_b32_e32 v162, 16, v86
	v_and_b32_e32 v163, 0xffff0000, v86
	v_lshlrev_b32_e32 v164, 16, v87
	v_and_b32_e32 v165, 0xffff0000, v87
	v_lshlrev_b32_e32 v166, 16, v88
	v_and_b32_e32 v167, 0xffff0000, v88
	v_lshlrev_b32_e32 v168, 16, v89
	v_and_b32_e32 v169, 0xffff0000, v89
	v_pk_fma_f32 v[154:155], v[42:43], v[66:67], v[154:155] op_sel_hi:[1,0,1]
	v_pk_fma_f32 v[156:157], v[44:45], v[66:67], v[156:157] op_sel_hi:[1,0,1]
	v_pk_fma_f32 v[158:159], v[46:47], v[66:67], v[158:159] op_sel_hi:[1,0,1]
	v_pk_fma_f32 v[160:161], v[48:49], v[66:67], v[160:161] op_sel_hi:[1,0,1]
	v_mul_f32_e32 v170, 0xbfb8aa3b, v162
	v_mul_f32_e32 v171, 0xbfb8aa3b, v163
	v_mul_f32_e32 v172, 0xbfb8aa3b, v164
	v_mul_f32_e32 v173, 0xbfb8aa3b, v165
	v_mul_f32_e32 v174, 0xbfb8aa3b, v166
	v_mul_f32_e32 v175, 0xbfb8aa3b, v167
	v_mul_f32_e32 v176, 0xbfb8aa3b, v168
	v_mul_f32_e32 v177, 0xbfb8aa3b, v169
	v_pk_mul_f32 v[154:155], v[0:1], v[154:155] op_sel_hi:[0,1]
	v_pk_mul_f32 v[156:157], v[0:1], v[156:157] op_sel_hi:[0,1]
	v_pk_mul_f32 v[158:159], v[0:1], v[158:159] op_sel_hi:[0,1]
	v_pk_mul_f32 v[160:161], v[0:1], v[160:161] op_sel_hi:[0,1]
	v_exp_f32_e32 v170, v170
	v_exp_f32_e32 v171, v171
	v_exp_f32_e32 v172, v172
	v_exp_f32_e32 v173, v173
	v_exp_f32_e32 v174, v174
	v_exp_f32_e32 v175, v175
	v_exp_f32_e32 v176, v176
	v_exp_f32_e32 v177, v177
	v_pk_add_f32 v[170:171], v[170:171], 1.0 op_sel_hi:[1,0]
	v_pk_add_f32 v[172:173], v[172:173], 1.0 op_sel_hi:[1,0]
	v_pk_add_f32 v[174:175], v[174:175], 1.0 op_sel_hi:[1,0]
	v_pk_add_f32 v[176:177], v[176:177], 1.0 op_sel_hi:[1,0]
	v_rcp_f32_e32 v170, v170
	v_rcp_f32_e32 v171, v171
	v_rcp_f32_e32 v172, v172
	v_rcp_f32_e32 v173, v173
	v_rcp_f32_e32 v174, v174
	v_rcp_f32_e32 v175, v175
	v_rcp_f32_e32 v176, v176
	v_rcp_f32_e32 v177, v177
	v_pk_mul_f32 v[162:163], v[162:163], v[170:171]
	v_pk_mul_f32 v[164:165], v[164:165], v[172:173]
	v_pk_mul_f32 v[166:167], v[166:167], v[174:175]
	v_pk_mul_f32 v[168:169], v[168:169], v[176:177]
	v_pk_mul_f32 v[154:155], v[162:163], v[154:155]
	v_pk_mul_f32 v[156:157], v[164:165], v[156:157]
	v_pk_mul_f32 v[158:159], v[166:167], v[158:159]
	v_pk_mul_f32 v[160:161], v[168:169], v[160:161]
	v_cvt_pk_bf16_f32 v102, v154, v155
	v_cvt_pk_bf16_f32 v103, v156, v157
	v_cvt_pk_bf16_f32 v104, v158, v159
	v_cvt_pk_bf16_f32 v105, v160, v161
	s_nop 1
	v_permlane32_swap_b32_e32 v102, v104
	v_permlane32_swap_b32_e32 v103, v105
	global_store_dwordx4 v[148:149], v[102:105], off offset:96

; DI void attn_unit(const Params& p, int b, int h, int qb, LAS unsigned char* lds, int tid, int lane, int wave) {
;     ...
;     __syncthreads();
;     if (g == 0) {
;         const float m1 = MB[64 * 64], l1 = MB[65 * 64];
;         const float m = fmaxf(mrow, m1);
;         const float a0 = __builtin_amdgcn_exp2f(mrow - m), a1 = __builtin_amdgcn_exp2f(m1 - m);
;         const float inv = 1.0f / (lrow * a0 + l1 * a1);
;         const size_t tok = tokb + qr0 + r;
;         const bf16_t* gp = Z + tok * ZLD + Z_MG + h * 128 + 4 * hh;
;         bf16_t* op = OB + tok * DM + 512 + h * 128 + 4 * hh;
;         u32x2 gw[4][4];
; #pragma unroll
;         for (int i = 0; i < 4; ++i)
; #pragma unroll
;             for (int q = 0; q < 4; ++q) gw[i][q] = *(const u32x2*)(gp + i * 32 + q * 8);
.Le2_wd:
	s_xor_b32 s0, s21, 1
	s_mulk_i32 s0, 0x2200
	v_add_u32_e32 v150, s0, v104
	s_waitcnt lgkmcnt(0)
	s_barrier
	ds_read2st64_b32 v[70:71], v150 offset0:32 offset1:33
	ds_read2st64_b32 v[110:111], v150 offset0:0 offset1:1
	ds_read2st64_b32 v[112:113], v150 offset0:2 offset1:3
	ds_read2st64_b32 v[114:115], v150 offset0:4 offset1:5
	ds_read2st64_b32 v[116:117], v150 offset0:6 offset1:7
	ds_read2st64_b32 v[118:119], v150 offset0:8 offset1:9
	ds_read2st64_b32 v[120:121], v150 offset0:10 offset1:11
	ds_read2st64_b32 v[122:123], v150 offset0:12 offset1:13
	ds_read2st64_b32 v[124:125], v150 offset0:14 offset1:15
	ds_read2st64_b32 v[126:127], v150 offset0:16 offset1:17
	ds_read2st64_b32 v[128:129], v150 offset0:18 offset1:19
	ds_read2st64_b32 v[130:131], v150 offset0:20 offset1:21
	ds_read2st64_b32 v[132:133], v150 offset0:22 offset1:23
	ds_read2st64_b32 v[134:135], v150 offset0:24 offset1:25
	ds_read2st64_b32 v[136:137], v150 offset0:26 offset1:27
	ds_read2st64_b32 v[138:139], v150 offset0:28 offset1:29
	ds_read2st64_b32 v[140:141], v150 offset0:30 offset1:31
	v_max_f32_e32 v0, v204, v204
	s_lshl_b32 s92, s2, 8
	v_ashrrev_i32_e32 v183, 31, v182
	v_lshlrev_b64 v[102:103], 1, v[182:183]
	s_waitcnt lgkmcnt(0)
	v_max_f32_e32 v66, v70, v70
	v_max_f32_e32 v0, v0, v66
	v_sub_f32_e32 v66, v204, v0
	v_sub_f32_e32 v0, v70, v0
	v_exp_f32_e32 v66, v66
	v_exp_f32_e32 v67, v0
	v_mov_b32_e32 v69, v71
	v_lshlrev_b32_e32 v0, 12, v202
	s_mov_b64 s[0:1], 0x4600c00
	v_pk_mul_f32 v[68:69], v[68:69], v[66:67]
	s_nop 0
	v_add_f32_e32 v105, v68, v69
	v_lshl_add_u64 v[68:69], s[50:51], 0, v[0:1]
	v_lshl_add_u64 v[70:71], v[68:69], 0, s[92:93]
	v_lshlrev_b32_e32 v0, 11, v202
	v_lshl_add_u64 v[70:71], v[70:71], 0, v[102:103]
	v_sub_co_u32_e32 v72, vcc, 0, v0
	v_lshl_add_u64 v[106:107], v[70:71], 0, s[0:1]
	s_nop 0
	v_subb_co_u32_e64 v73, s[0:1], 0, 0, vcc
	s_mov_b32 s0, 0x4600000
	s_nop 0
	v_add_co_u32_e32 v70, vcc, s0, v70
	v_lshl_add_u64 v[68:69], v[68:69], 0, v[72:73]
	s_nop 0
	v_addc_co_u32_e32 v71, vcc, 0, v71, vcc
	s_lshl_b32 vcc_lo, s21, 7
	s_mov_b32 vcc_hi, 0
	v_lshl_add_u64 v[142:143], v[106:107], 0, vcc
	v_lshl_add_u32 v152, v182, 1, vcc_lo
	global_load_dwordx2 v[74:75], v[142:143], off
	global_load_dwordx2 v[76:77], v[142:143], off offset:16
	global_load_dwordx2 v[78:79], v[142:143], off offset:32
	global_load_dwordx2 v[80:81], v[142:143], off offset:48
	global_load_dwordx2 v[82:83], v[142:143], off offset:64
	global_load_dwordx2 v[84:85], v[142:143], off offset:80
	global_load_dwordx2 v[86:87], v[142:143], off offset:96
	global_load_dwordx2 v[88:89], v[142:143], off offset:112
	v_div_scale_f32 v0, s[0:1], v105, v105, 1.0
	v_rcp_f32_e32 v106, v0
	v_lshl_add_u64 v[68:69], v[68:69], 0, s[92:93]
	v_lshl_add_u64 v[102:103], v[68:69], 0, v[102:103]
	s_mov_b64 s[0:1], 0xae00400
	v_fma_f32 v107, -v0, v106, 1.0
	v_fmac_f32_e32 v106, v107, v106
	v_div_scale_f32 v107, vcc, 1.0, v105, 1.0
	v_mul_f32_e32 v108, v107, v106
	v_fma_f32 v109, -v0, v108, v107
	v_fmac_f32_e32 v108, v109, v106
	v_fma_f32 v0, -v0, v108, v107
	v_div_fmas_f32 v0, v0, v106, v108
	v_div_fixup_f32 v0, v0, v105, 1.0
	v_lshl_add_u64 v[68:69], v[102:103], 0, s[0:1]
	v_mov_b32_e32 v72, v67
	v_mov_b32_e32 v153, 0
	v_lshl_add_u64 v[148:149], v[152:153], 0, v[68:69]
	s_waitcnt vmcnt(6)
	v_pk_mul_f32 v[154:155], v[72:73], v[110:111] op_sel_hi:[0,1]
	v_pk_mul_f32 v[156:157], v[72:73], v[112:113] op_sel_hi:[0,1]
	v_pk_mul_f32 v[158:159], v[72:73], v[114:115] op_sel_hi:[0,1]
	v_pk_mul_f32 v[160:161], v[72:73], v[116:117] op_sel_hi:[0,1]
	v_lshlrev_b32_e32 v162, 16, v74
	v_and_b32_e32 v163, 0xffff0000, v74
	v_lshlrev_b32_e32 v164, 16, v75
	v_and_b32_e32 v165, 0xffff0000, v75
	v_lshlrev_b32_e32 v166, 16, v76
	v_and_b32_e32 v167, 0xffff0000, v76
	v_lshlrev_b32_e32 v168, 16, v77
	v_and_b32_e32 v169, 0xffff0000, v77
	v_pk_fma_f32 v[154:155], v[50:51], v[66:67], v[154:155] op_sel_hi:[1,0,1]
	v_pk_fma_f32 v[156:157], v[52:53], v[66:67], v[156:157] op_sel_hi:[1,0,1]
	v_pk_fma_f32 v[158:159], v[54:55], v[66:67], v[158:159] op_sel_hi:[1,0,1]
	v_pk_fma_f32 v[160:161], v[56:57], v[66:67], v[160:161] op_sel_hi:[1,0,1]
	v_mul_f32_e32 v170, 0xbfb8aa3b, v162
	v_mul_f32_e32 v171, 0xbfb8aa3b, v163
	v_mul_f32_e32 v172, 0xbfb8aa3b, v164
	v_mul_f32_e32 v173, 0xbfb8aa3b, v165
	v_mul_f32_e32 v174, 0xbfb8aa3b, v166
	v_mul_f32_e32 v175, 0xbfb8aa3b, v167
	v_mul_f32_e32 v176, 0xbfb8aa3b, v168
	v_mul_f32_e32 v177, 0xbfb8aa3b, v169
	v_pk_mul_f32 v[154:155], v[0:1], v[154:155] op_sel_hi:[0,1]
	v_pk_mul_f32 v[156:157], v[0:1], v[156:157] op_sel_hi:[0,1]
	v_pk_mul_f32 v[158:159], v[0:1], v[158:159] op_sel_hi:[0,1]
	v_pk_mul_f32 v[160:161], v[0:1], v[160:161] op_sel_hi:[0,1]
	v_exp_f32_e32 v170, v170
	v_exp_f32_e32 v171, v171
	v_exp_f32_e32 v172, v172
	v_exp_f32_e32 v173, v173
	v_exp_f32_e32 v174, v174
	v_exp_f32_e32 v175, v175
	v_exp_f32_e32 v176, v176
	v_exp_f32_e32 v177, v177
	v_pk_add_f32 v[170:171], v[170:171], 1.0 op_sel_hi:[1,0]
	v_pk_add_f32 v[172:173], v[172:173], 1.0 op_sel_hi:[1,0]
	v_pk_add_f32 v[174:175], v[174:175], 1.0 op_sel_hi:[1,0]
	v_pk_add_f32 v[176:177], v[176:177], 1.0 op_sel_hi:[1,0]
	v_rcp_f32_e32 v170, v170
	v_rcp_f32_e32 v171, v171
	v_rcp_f32_e32 v172, v172
	v_rcp_f32_e32 v173, v173
	v_rcp_f32_e32 v174, v174
	v_rcp_f32_e32 v175, v175
	v_rcp_f32_e32 v176, v176
	v_rcp_f32_e32 v177, v177
	v_pk_mul_f32 v[162:163], v[162:163], v[170:171]
	v_pk_mul_f32 v[164:165], v[164:165], v[172:173]
	v_pk_mul_f32 v[166:167], v[166:167], v[174:175]
	v_pk_mul_f32 v[168:169], v[168:169], v[176:177]
	v_pk_mul_f32 v[154:155], v[162:163], v[154:155]
	v_pk_mul_f32 v[156:157], v[164:165], v[156:157]
	v_pk_mul_f32 v[158:159], v[166:167], v[158:159]
	v_pk_mul_f32 v[160:161], v[168:169], v[160:161]
	v_cvt_pk_bf16_f32 v90, v154, v155
	v_cvt_pk_bf16_f32 v91, v156, v157
	v_cvt_pk_bf16_f32 v92, v158, v159
	v_cvt_pk_bf16_f32 v93, v160, v161
	s_nop 1
	v_permlane32_swap_b32_e32 v90, v92
	v_permlane32_swap_b32_e32 v91, v93
	global_store_dwordx4 v[148:149], v[90:93], off
	s_waitcnt vmcnt(5)
; DI unsigned pk2(float lo, float hi) { f32x2 v = {lo, hi}; return __builtin_bit_cast(unsigned, __builtin_convertvector(v, bf2_t)); }
; DI float bflo(unsigned w) { return __uint_as_float(w << 16); }
; DI float bfhi(unsigned w) { return __uint_as_float(w & 0xffff0000u); }
; DI void attn_unit(const Params& p, int b, int h, int qb, LAS unsigned char* lds, int tid, int lane, int wave) {
;     ...
; #pragma unroll
;         for (int i = 0; i < 4; ++i)
; #pragma unroll
;             for (int q = 0; q < 4; ++q) {
;                 float gv[4] = {bflo(gw[i][q].x), bfhi(gw[i][q].x), bflo(gw[i][q].y), bfhi(gw[i][q].y)}; float ov[4];
; #pragma unroll
;                 for (int e = 0; e < 4; ++e) { const float val = (o[i][q * 4 + e] * a0 + MB[(i * 16 + q * 4 + e) * 64] * a1) * inv; ov[e] = val * (gv[e] / (1.f + __expf(-gv[e]))); }
;                 *(u32x2*)(op + i * 32 + q * 8) = (u32x2){pk2(ov[0], ov[1]), pk2(ov[2], ov[3])};
;             }
	v_pk_mul_f32 v[154:155], v[72:73], v[118:119] op_sel_hi:[0,1]
	v_pk_mul_f32 v[156:157], v[72:73], v[120:121] op_sel_hi:[0,1]
	v_pk_mul_f32 v[158:159], v[72:73], v[122:123] op_sel_hi:[0,1]
	v_pk_mul_f32 v[160:161], v[72:73], v[124:125] op_sel_hi:[0,1]
	v_lshlrev_b32_e32 v162, 16, v78
	v_and_b32_e32 v163, 0xffff0000, v78
	v_lshlrev_b32_e32 v164, 16, v79
	v_and_b32_e32 v165, 0xffff0000, v79
	v_lshlrev_b32_e32 v166, 16, v80
	v_and_b32_e32 v167, 0xffff0000, v80
	v_lshlrev_b32_e32 v168, 16, v81
	v_and_b32_e32 v169, 0xffff0000, v81
	v_pk_fma_f32 v[154:155], v[58:59], v[66:67], v[154:155] op_sel_hi:[1,0,1]
	v_pk_fma_f32 v[156:157], v[60:61], v[66:67], v[156:157] op_sel_hi:[1,0,1]
	v_pk_fma_f32 v[158:159], v[62:63], v[66:67], v[158:159] op_sel_hi:[1,0,1]
	v_pk_fma_f32 v[160:161], v[64:65], v[66:67], v[160:161] op_sel_hi:[1,0,1]
	v_mul_f32_e32 v170, 0xbfb8aa3b, v162
	v_mul_f32_e32 v171, 0xbfb8aa3b, v163
	v_mul_f32_e32 v172, 0xbfb8aa3b, v164
	v_mul_f32_e32 v173, 0xbfb8aa3b, v165
	v_mul_f32_e32 v174, 0xbfb8aa3b, v166
	v_mul_f32_e32 v175, 0xbfb8aa3b, v167
	v_mul_f32_e32 v176, 0xbfb8aa3b, v168
	v_mul_f32_e32 v177, 0xbfb8aa3b, v169
	v_pk_mul_f32 v[154:155], v[0:1], v[154:155] op_sel_hi:[0,1]
	v_pk_mul_f32 v[156:157], v[0:1], v[156:157] op_sel_hi:[0,1]
	v_pk_mul_f32 v[158:159], v[0:1], v[158:159] op_sel_hi:[0,1]
	v_pk_mul_f32 v[160:161], v[0:1], v[160:161] op_sel_hi:[0,1]
	v_exp_f32_e32 v170, v170
	v_exp_f32_e32 v171, v171
	v_exp_f32_e32 v172, v172
	v_exp_f32_e32 v173, v173
	v_exp_f32_e32 v174, v174
	v_exp_f32_e32 v175, v175
	v_exp_f32_e32 v176, v176
	v_exp_f32_e32 v177, v177
	v_pk_add_f32 v[170:171], v[170:171], 1.0 op_sel_hi:[1,0]
	v_pk_add_f32 v[172:173], v[172:173], 1.0 op_sel_hi:[1,0]
	v_pk_add_f32 v[174:175], v[174:175], 1.0 op_sel_hi:[1,0]
	v_pk_add_f32 v[176:177], v[176:177], 1.0 op_sel_hi:[1,0]
	v_rcp_f32_e32 v170, v170
	v_rcp_f32_e32 v171, v171
	v_rcp_f32_e32 v172, v172
	v_rcp_f32_e32 v173, v173
	v_rcp_f32_e32 v174, v174
	v_rcp_f32_e32 v175, v175
	v_rcp_f32_e32 v176, v176
	v_rcp_f32_e32 v177, v177
	v_pk_mul_f32 v[162:163], v[162:163], v[170:171]
	v_pk_mul_f32 v[164:165], v[164:165], v[172:173]
	v_pk_mul_f32 v[166:167], v[166:167], v[174:175]
	v_pk_mul_f32 v[168:169], v[168:169], v[176:177]
	v_pk_mul_f32 v[154:155], v[162:163], v[154:155]
	v_pk_mul_f32 v[156:157], v[164:165], v[156:157]
	v_pk_mul_f32 v[158:159], v[166:167], v[158:159]
	v_pk_mul_f32 v[160:161], v[168:169], v[160:161]
	v_cvt_pk_bf16_f32 v94, v154, v155
	v_cvt_pk_bf16_f32 v95, v156, v157
	v_cvt_pk_bf16_f32 v96, v158, v159
	v_cvt_pk_bf16_f32 v97, v160, v161
	s_nop 1
	v_permlane32_swap_b32_e32 v94, v96
	v_permlane32_swap_b32_e32 v95, v97
	global_store_dwordx4 v[148:149], v[94:97], off offset:32
	s_waitcnt vmcnt(4)
	v_pk_mul_f32 v[154:155], v[72:73], v[126:127] op_sel_hi:[0,1]
	v_pk_mul_f32 v[156:157], v[72:73], v[128:129] op_sel_hi:[0,1]
	v_pk_mul_f32 v[158:159], v[72:73], v[130:131] op_sel_hi:[0,1]
	v_pk_mul_f32 v[160:161], v[72:73], v[132:133] op_sel_hi:[0,1]
	v_lshlrev_b32_e32 v162, 16, v82
	v_and_b32_e32 v163, 0xffff0000, v82
	v_lshlrev_b32_e32 v164, 16, v83
	v_and_b32_e32 v165, 0xffff0000, v83
	v_lshlrev_b32_e32 v166, 16, v84
	v_and_b32_e32 v167, 0xffff0000, v84
	v_lshlrev_b32_e32 v168, 16, v85
	v_and_b32_e32 v169, 0xffff0000, v85
	v_pk_fma_f32 v[154:155], v[34:35], v[66:67], v[154:155] op_sel_hi:[1,0,1]
	v_pk_fma_f32 v[156:157], v[36:37], v[66:67], v[156:157] op_sel_hi:[1,0,1]
	v_pk_fma_f32 v[158:159], v[38:39], v[66:67], v[158:159] op_sel_hi:[1,0,1]
	v_pk_fma_f32 v[160:161], v[40:41], v[66:67], v[160:161] op_sel_hi:[1,0,1]
	v_mul_f32_e32 v170, 0xbfb8aa3b, v162
	v_mul_f32_e32 v171, 0xbfb8aa3b, v163
	v_mul_f32_e32 v172, 0xbfb8aa3b, v164
	v_mul_f32_e32 v173, 0xbfb8aa3b, v165
	v_mul_f32_e32 v174, 0xbfb8aa3b, v166
	v_mul_f32_e32 v175, 0xbfb8aa3b, v167
	v_mul_f32_e32 v176, 0xbfb8aa3b, v168
	v_mul_f32_e32 v177, 0xbfb8aa3b, v169
	v_pk_mul_f32 v[154:155], v[0:1], v[154:155] op_sel_hi:[0,1]
	v_pk_mul_f32 v[156:157], v[0:1], v[156:157] op_sel_hi:[0,1]
	v_pk_mul_f32 v[158:159], v[0:1], v[158:159] op_sel_hi:[0,1]
	v_pk_mul_f32 v[160:161], v[0:1], v[160:161] op_sel_hi:[0,1]
	v_exp_f32_e32 v170, v170
	v_exp_f32_e32 v171, v171
	v_exp_f32_e32 v172, v172
	v_exp_f32_e32 v173, v173
	v_exp_f32_e32 v174, v174
	v_exp_f32_e32 v175, v175
	v_exp_f32_e32 v176, v176
	v_exp_f32_e32 v177, v177
	v_pk_add_f32 v[170:171], v[170:171], 1.0 op_sel_hi:[1,0]
	v_pk_add_f32 v[172:173], v[172:173], 1.0 op_sel_hi:[1,0]
	v_pk_add_f32 v[174:175], v[174:175], 1.0 op_sel_hi:[1,0]
	v_pk_add_f32 v[176:177], v[176:177], 1.0 op_sel_hi:[1,0]
	v_rcp_f32_e32 v170, v170
	v_rcp_f32_e32 v171, v171
	v_rcp_f32_e32 v172, v172
	v_rcp_f32_e32 v173, v173
	v_rcp_f32_e32 v174, v174
	v_rcp_f32_e32 v175, v175
	v_rcp_f32_e32 v176, v176
	v_rcp_f32_e32 v177, v177
	v_pk_mul_f32 v[162:163], v[162:163], v[170:171]
	v_pk_mul_f32 v[164:165], v[164:165], v[172:173]
	v_pk_mul_f32 v[166:167], v[166:167], v[174:175]
	v_pk_mul_f32 v[168:169], v[168:169], v[176:177]
	v_pk_mul_f32 v[154:155], v[162:163], v[154:155]
	v_pk_mul_f32 v[156:157], v[164:165], v[156:157]
	v_pk_mul_f32 v[158:159], v[166:167], v[158:159]
	v_pk_mul_f32 v[160:161], v[168:169], v[160:161]
	v_cvt_pk_bf16_f32 v98, v154, v155
	v_cvt_pk_bf16_f32 v99, v156, v157
	v_cvt_pk_bf16_f32 v100, v158, v159
	v_cvt_pk_bf16_f32 v101, v160, v161
	s_nop 1
	v_permlane32_swap_b32_e32 v98, v100
	v_permlane32_swap_b32_e32 v99, v101
	global_store_dwordx4 v[148:149], v[98:101], off offset:64
	s_waitcnt vmcnt(3)
; DI unsigned pk2(float lo, float hi) { f32x2 v = {lo, hi}; return __builtin_bit_cast(unsigned, __builtin_convertvector(v, bf2_t)); }
; DI float bflo(unsigned w) { return __uint_as_float(w << 16); }
; DI float bfhi(unsigned w) { return __uint_as_float(w & 0xffff0000u); }
; DI void attn_unit(const Params& p, int b, int h, int qb, LAS unsigned char* lds, int tid, int lane, int wave) {
;     ...
; #pragma unroll
;         for (int i = 0; i < 4; ++i)
; #pragma unroll
;             for (int q = 0; q < 4; ++q) {
;                 float gv[4] = {bflo(gw[i][q].x), bfhi(gw[i][q].x), bflo(gw[i][q].y), bfhi(gw[i][q].y)}; float ov[4];
; #pragma unroll
;                 for (int e = 0; e < 4; ++e) { const float val = (o[i][q * 4 + e] * a0 + MB[(i * 16 + q * 4 + e) * 64] * a1) * inv; ov[e] = val * (gv[e] / (1.f + __expf(-gv[e]))); }
;                 *(u32x2*)(op + i * 32 + q * 8) = (u32x2){pk2(ov[0], ov[1]), pk2(ov[2], ov[3])};
;             }
	v_pk_mul_f32 v[154:155], v[72:73], v[134:135] op_sel_hi:[0,1]
	v_pk_mul_f32 v[156:157], v[72:73], v[136:137] op_sel_hi:[0,1]
	v_pk_mul_f32 v[158:159], v[72:73], v[138:139] op_sel_hi:[0,1]
	v_pk_mul_f32 v[160:161], v[72:73], v[140:141] op_sel_hi:[0,1]
	v_lshlrev_b32_e32 v162, 16, v86
	v_and_b32_e32 v163, 0xffff0000, v86
	v_lshlrev_b32_e32 v164, 16, v87
	v_and_b32_e32 v165, 0xffff0000, v87
	v_lshlrev_b32_e32 v166, 16, v88
	v_and_b32_e32 v167, 0xffff0000, v88
	v_lshlrev_b32_e32 v168, 16, v89
	v_and_b32_e32 v169, 0xffff0000, v89
	v_pk_fma_f32 v[154:155], v[42:43], v[66:67], v[154:155] op_sel_hi:[1,0,1]
	v_pk_fma_f32 v[156:157], v[44:45], v[66:67], v[156:157] op_sel_hi:[1,0,1]
	v_pk_fma_f32 v[158:159], v[46:47], v[66:67], v[158:159] op_sel_hi:[1,0,1]
	v_pk_fma_f32 v[160:161], v[48:49], v[66:67], v[160:161] op_sel_hi:[1,0,1]
	v_mul_f32_e32 v170, 0xbfb8aa3b, v162
	v_mul_f32_e32 v171, 0xbfb8aa3b, v163
	v_mul_f32_e32 v172, 0xbfb8aa3b, v164
	v_mul_f32_e32 v173, 0xbfb8aa3b, v165
	v_mul_f32_e32 v174, 0xbfb8aa3b, v166
	v_mul_f32_e32 v175, 0xbfb8aa3b, v167
	v_mul_f32_e32 v176, 0xbfb8aa3b, v168
	v_mul_f32_e32 v177, 0xbfb8aa3b, v169
	v_pk_mul_f32 v[154:155], v[0:1], v[154:155] op_sel_hi:[0,1]
	v_pk_mul_f32 v[156:157], v[0:1], v[156:157] op_sel_hi:[0,1]
	v_pk_mul_f32 v[158:159], v[0:1], v[158:159] op_sel_hi:[0,1]
	v_pk_mul_f32 v[160:161], v[0:1], v[160:161] op_sel_hi:[0,1]
	v_exp_f32_e32 v170, v170
	v_exp_f32_e32 v171, v171
	v_exp_f32_e32 v172, v172
	v_exp_f32_e32 v173, v173
	v_exp_f32_e32 v174, v174
	v_exp_f32_e32 v175, v175
	v_exp_f32_e32 v176, v176
	v_exp_f32_e32 v177, v177
	v_pk_add_f32 v[170:171], v[170:171], 1.0 op_sel_hi:[1,0]
	v_pk_add_f32 v[172:173], v[172:173], 1.0 op_sel_hi:[1,0]
	v_pk_add_f32 v[174:175], v[174:175], 1.0 op_sel_hi:[1,0]
	v_pk_add_f32 v[176:177], v[176:177], 1.0 op_sel_hi:[1,0]
	v_rcp_f32_e32 v170, v170
	v_rcp_f32_e32 v171, v171
	v_rcp_f32_e32 v172, v172
	v_rcp_f32_e32 v173, v173
	v_rcp_f32_e32 v174, v174
	v_rcp_f32_e32 v175, v175
	v_rcp_f32_e32 v176, v176
	v_rcp_f32_e32 v177, v177
	v_pk_mul_f32 v[162:163], v[162:163], v[170:171]
	v_pk_mul_f32 v[164:165], v[164:165], v[172:173]
	v_pk_mul_f32 v[166:167], v[166:167], v[174:175]
	v_pk_mul_f32 v[168:169], v[168:169], v[176:177]
	v_pk_mul_f32 v[154:155], v[162:163], v[154:155]
	v_pk_mul_f32 v[156:157], v[164:165], v[156:157]
	v_pk_mul_f32 v[158:159], v[166:167], v[158:159]
	v_pk_mul_f32 v[160:161], v[168:169], v[160:161]
	v_cvt_pk_bf16_f32 v102, v154, v155
	v_cvt_pk_bf16_f32 v103, v156, v157
	v_cvt_pk_bf16_f32 v104, v158, v159
	v_cvt_pk_bf16_f32 v105, v160, v161
	s_nop 1
	v_permlane32_swap_b32_e32 v102, v104
	v_permlane32_swap_b32_e32 v103, v105
	global_store_dwordx4 v[148:149], v[102:105], off offset:96
	s_branch .LBB0_425
